# P7 ffnfix: both loops issue all loads up front (weights hoisted, split-K partial rows loaded in parallel, single wait), same add order
# baseline (speedup 1.0000x reference)
.LBB0_1054:
	s_or_b64 exec, exec, s[0:1]
	s_waitcnt vmcnt(6)
	v_pk_fma_f32 v[28:29], v[28:29], v[32:33], v[44:45]
	v_pk_fma_f32 v[30:31], v[30:31], v[34:35], v[46:47]
	v_pk_fma_f32 v[24:25], v[24:25], v[40:41], v[28:29]
	v_pk_fma_f32 v[26:27], v[26:27], v[42:43], v[30:31]
	v_pk_fma_f32 v[20:21], v[20:21], v[36:37], v[24:25]
	v_pk_fma_f32 v[22:23], v[22:23], v[38:39], v[26:27]
	v_mul_f32_e32 v24, 0x3d372713, v20
	v_mul_f32_e32 v24, v20, v24
	v_fma_f32 v24, v20, v24, v20
	v_mul_f32_e32 v24, 0x3fcc422a, v24
	v_mul_f32_e32 v24, 0xbfb8aa3b, v24
	v_exp_f32_e32 v24, v24
	v_lshl_add_u64 v[54:55], v[54:55], 0, s[54:55]
	s_mov_b64 s[0:1], 0x2ffff
	v_lshlrev_b32_e32 v48, 1, v48
	v_add_f32_e32 v24, 1.0, v24
	v_rcp_f32_e32 v24, v24
	v_cmp_lt_u64_e32 vcc, s[0:1], v[54:55]
	s_or_b64 s[44:45], vcc, s[44:45]
	v_mul_f32_e32 v20, v20, v24
	v_mul_f32_e32 v20, v16, v20
	v_mul_f32_e32 v16, 0x3d372713, v21
	v_mul_f32_e32 v16, v21, v16
	v_fma_f32 v16, v21, v16, v21
	v_mul_f32_e32 v16, 0x3fcc422a, v16
	v_mul_f32_e32 v16, 0xbfb8aa3b, v16
	v_exp_f32_e32 v16, v16
	s_nop 0
	v_add_f32_e32 v16, 1.0, v16
	v_rcp_f32_e32 v16, v16
	s_nop 0
	v_mul_f32_e32 v16, v21, v16
	v_mul_f32_e32 v21, v17, v16
	v_mul_f32_e32 v16, 0x3d372713, v22
	v_mul_f32_e32 v17, 0x3d372713, v23
	v_mul_f32_e32 v16, v22, v16
	v_mul_f32_e32 v17, v23, v17
	v_fma_f32 v16, v22, v16, v22
	v_fma_f32 v17, v23, v17, v23
	v_mul_f32_e32 v16, 0x3fcc422a, v16
	v_mul_f32_e32 v17, 0x3fcc422a, v17
	v_mul_f32_e32 v16, 0xbfb8aa3b, v16
	v_mul_f32_e32 v17, 0xbfb8aa3b, v17
	v_exp_f32_e32 v16, v16
	v_exp_f32_e32 v17, v17
	v_add_f32_e32 v16, 1.0, v16
	v_add_f32_e32 v17, 1.0, v17
	v_rcp_f32_e32 v16, v16
	v_rcp_f32_e32 v17, v17
	v_mul_f32_e32 v16, v22, v16
	v_mul_f32_e32 v17, v23, v17
	v_mul_f32_e32 v16, v18, v16
	v_mul_f32_e32 v17, v19, v17
	s_waitcnt vmcnt(0)
	v_pk_fma_f32 v[12:13], v[12:13], v[68:69], v[80:81]
	s_nop 0
	v_pk_fma_f32 v[8:9], v[8:9], v[72:73], v[12:13]
	v_pk_fma_f32 v[14:15], v[14:15], v[70:71], v[82:83]
	v_pk_fma_f32 v[4:5], v[4:5], v[76:77], v[8:9]
	v_pk_fma_f32 v[10:11], v[10:11], v[74:75], v[14:15]
	v_mul_f32_e32 v8, 0x3d372713, v4
	v_mul_f32_e32 v8, v4, v8
	v_fma_f32 v8, v4, v8, v4
	v_mul_f32_e32 v8, 0x3fcc422a, v8
	v_mul_f32_e32 v8, 0xbfb8aa3b, v8
	v_exp_f32_e32 v8, v8
	v_pk_fma_f32 v[6:7], v[6:7], v[78:79], v[10:11]
	v_add_f32_e32 v8, 1.0, v8
	v_rcp_f32_e32 v8, v8
	s_nop 0
	v_mul_f32_e32 v4, v4, v8
	v_mul_f32_e32 v0, v0, v4
	v_mul_f32_e32 v4, 0x3d372713, v5
	v_mul_f32_e32 v4, v5, v4
	v_fma_f32 v4, v5, v4, v5
	v_mul_f32_e32 v4, 0x3fcc422a, v4
	v_mul_f32_e32 v4, 0xbfb8aa3b, v4
	v_exp_f32_e32 v4, v4
	s_nop 0
	v_add_f32_e32 v4, 1.0, v4
	v_rcp_f32_e32 v4, v4
	s_nop 0
	v_mul_f32_e32 v4, v5, v4
	v_mul_f32_e32 v1, v1, v4
	v_mul_f32_e32 v4, 0x3d372713, v6
	v_mul_f32_e32 v4, v6, v4
	v_fma_f32 v4, v6, v4, v6
	v_mul_f32_e32 v4, 0x3fcc422a, v4
	v_mul_f32_e32 v4, 0xbfb8aa3b, v4
	v_exp_f32_e32 v4, v4
	s_nop 0
	v_add_f32_e32 v4, 1.0, v4
	v_rcp_f32_e32 v4, v4
	s_nop 0
	v_mul_f32_e32 v4, v6, v4
	v_mul_f32_e32 v2, v2, v4
	v_mul_f32_e32 v4, 0x3d372713, v7
	v_mul_f32_e32 v4, v7, v4
	v_fma_f32 v4, v7, v4, v7
	v_mul_f32_e32 v4, 0x3fcc422a, v4
	v_mul_f32_e32 v4, 0xbfb8aa3b, v4
	v_exp_f32_e32 v4, v4
	s_nop 0
	v_add_f32_e32 v4, 1.0, v4
	v_rcp_f32_e32 v4, v4
	s_nop 0
	v_mul_f32_e32 v4, v7, v4
	v_mul_f32_e32 v3, v3, v4
	v_cvt_pk_bf16_f32 v4, v20, v21
	v_cvt_pk_bf16_f32 v5, v16, v17
	v_cvt_pk_bf16_f32 v6, v0, v1
	v_mul_u32_u24_e32 v0, 0xc00, v66
	v_mov_b32_e32 v1, v49
	v_lshl_add_u64 v[0:1], v[0:1], 1, s[86:87]
	v_lshl_add_u64 v[0:1], v[0:1], 0, v[48:49]
	v_cvt_pk_bf16_f32 v7, v2, v3
	global_store_dwordx4 v[0:1], v[4:7], off
	s_andn2_b64 exec, exec, s[44:45]
	s_cbranch_execz .LBB0_1071

.LBB0_1057:
	s_or_saveexec_b64 s[50:51], s[34:35]
	v_mov_b32_e32 v7, v49
	v_lshl_add_u64 v[6:7], v[6:7], 0, s[46:47]
	v_and_b32_e32 v7, 3, v7
	v_mad_u64_u32 v[62:63], s[4:5], v6, s2, v[50:51]
	v_mad_u32_u24 v63, v7, s2, v63
	s_mov_b64 s[4:5], 0x9000
	v_lshl_add_u64 v[14:15], v[62:63], 0, s[4:5]
	s_and_b64 s[0:1], s[0:1], s[42:43]
	v_mov_b64_e32 v[6:7], 0x9000
	s_xor_b64 exec, exec, s[50:51]
	s_cbranch_execz .LBB0_1061
	s_nop 0
	v_mov_b32_e32 v24, v49
	v_mov_b32_e32 v25, v49
	v_mov_b32_e32 v26, v49
	v_mov_b32_e32 v27, v49
	s_and_saveexec_b64 s[34:35], s[0:1]
	s_cbranch_execz .LBB0_1060
	v_lshl_add_u64 v[6:7], v[48:49], 2, v[14:15]
	global_load_dwordx4 v[24:27], v[6:7], off

.LBB0_1063:
	s_or_b64 exec, exec, s[34:35]
	v_lshl_add_u64 v[58:59], s[74:75], 0, v[4:5]
	v_lshl_add_u64 v[6:7], s[36:37], 0, v[4:5]
	v_lshl_add_u64 v[56:57], s[76:77], 0, v[4:5]
	global_load_dwordx4 v[32:35], v[58:59], off
	v_lshl_add_u64 v[8:9], s[58:59], 0, v[4:5]
	global_load_dwordx4 v[40:43], v[6:7], off
	global_load_dwordx4 v[36:39], v[8:9], off
	global_load_dwordx4 v[44:47], v[56:57], off
	global_load_dwordx4 v[68:71], v[58:59], off offset:16
	global_load_dwordx4 v[72:75], v[6:7], off offset:16
	global_load_dwordx4 v[76:79], v[8:9], off offset:16
	global_load_dwordx4 v[80:83], v[56:57], off offset:16
	s_nop 0
	global_load_dwordx4 v[4:7], v[0:1], off offset:16
	s_nop 0
	global_load_dwordx4 v[0:3], v[2:3], off offset:16
	s_mov_b64 s[42:43], 0
	s_and_saveexec_b64 s[4:5], vcc
	s_xor_b64 s[34:35], exec, s[4:5]
	s_cbranch_execz .LBB0_1065
	global_load_dwordx4 v[8:11], v[12:13], off offset:16
	s_and_b64 s[42:43], s[26:27], exec
.LBB0_1065:
	s_or_saveexec_b64 s[48:49], s[34:35]
	v_or_b32_e32 v60, 4, v48
	v_mov_b32_e32 v61, v49
	v_mov_b64_e32 v[64:65], 0x9000
	s_xor_b64 exec, exec, s[48:49]
	s_cbranch_execz .LBB0_1069
	s_nop 0
	v_mov_b32_e32 v8, v49
	v_mov_b32_e32 v9, v49
	v_mov_b32_e32 v10, v49
	v_mov_b32_e32 v11, v49
	s_and_saveexec_b64 s[34:35], s[0:1]
	s_cbranch_execz .LBB0_1068
	v_lshl_add_u64 v[8:9], v[60:61], 2, v[14:15]
	global_load_dwordx4 v[8:11], v[8:9], off

.LBB0_1072:
	s_or_b64 exec, exec, s[34:35]
	v_pk_add_f32 v[4:5], v[4:5], v[8:9]
	v_pk_add_f32 v[6:7], v[6:7], v[10:11]
	v_pk_add_f32 v[4:5], v[4:5], v[12:13]
	v_pk_add_f32 v[6:7], v[6:7], v[14:15]
	v_pk_add_f32 v[4:5], v[4:5], v[16:17]
	v_pk_add_f32 v[6:7], v[6:7], v[18:19]
	s_nop 0
	v_pk_add_f32 v[20:21], v[4:5], v[20:21]
	v_pk_add_f32 v[22:23], v[6:7], v[22:23]
	v_mul_u32_u24_e32 v48, 0xc00, v57
	v_lshl_add_u64 v[180:181], v[180:181], 0, s[54:55]
	s_mov_b64 s[6:7], 0x2ffff
	v_cmp_lt_u64_e32 vcc, s[6:7], v[180:181]
	v_add_u32_e32 v185, s2, v185
	v_add_u32_e32 v56, s3, v56
	s_or_b64 s[46:47], vcc, s[46:47]
	s_nop 0
	v_pk_fma_f32 v[4:5], v[44:45], v[100:101], v[104:105]
	v_pk_fma_f32 v[6:7], v[46:47], v[102:103], v[106:107]
	s_nop 0
	v_pk_fma_f32 v[4:5], v[40:41], v[108:109], v[4:5]
	v_pk_fma_f32 v[6:7], v[42:43], v[110:111], v[6:7]
	s_nop 0
	v_pk_fma_f32 v[0:1], v[0:1], v[112:113], v[4:5]
	v_pk_fma_f32 v[2:3], v[2:3], v[114:115], v[6:7]
	v_mul_f32_e32 v4, 0x3d372713, v0
	v_mul_f32_e32 v4, v0, v4
	v_fma_f32 v4, v0, v4, v0
	v_mul_f32_e32 v4, 0x3fcc422a, v4
	v_mul_f32_e32 v4, 0xbfb8aa3b, v4
	v_exp_f32_e32 v4, v4
	s_nop 0
	v_add_f32_e32 v4, 1.0, v4
	v_rcp_f32_e32 v4, v4
	s_nop 0
	v_mul_f32_e32 v0, v0, v4
	v_mul_f32_e32 v4, 0x3d372713, v1
	v_mul_f32_e32 v4, v1, v4
	v_fma_f32 v4, v1, v4, v1
	v_mul_f32_e32 v4, 0x3fcc422a, v4
	v_mul_f32_e32 v4, 0xbfb8aa3b, v4
	v_exp_f32_e32 v4, v4
	v_mul_f32_e32 v0, v20, v0
	v_add_f32_e32 v4, 1.0, v4
	v_rcp_f32_e32 v4, v4
	s_nop 0
	v_mul_f32_e32 v1, v1, v4
	v_mul_f32_e32 v1, v21, v1
	v_cvt_pk_bf16_f32 v0, v0, v1
	v_mul_f32_e32 v1, 0x3d372713, v2
	v_mul_f32_e32 v1, v2, v1
	v_fma_f32 v1, v2, v1, v2
	v_mul_f32_e32 v1, 0x3fcc422a, v1
	v_mul_f32_e32 v1, 0xbfb8aa3b, v1
	v_exp_f32_e32 v1, v1
	s_nop 0
	v_add_f32_e32 v1, 1.0, v1
	v_rcp_f32_e32 v1, v1
	s_nop 0
	v_mul_f32_e32 v1, v2, v1
	v_mul_f32_e32 v2, 0x3d372713, v3
	v_mul_f32_e32 v2, v3, v2
	v_fma_f32 v2, v3, v2, v3
	v_mul_f32_e32 v2, 0x3fcc422a, v2
	v_mul_f32_e32 v2, 0xbfb8aa3b, v2
	v_exp_f32_e32 v2, v2
	v_mul_f32_e32 v1, v22, v1
	v_add_f32_e32 v2, 1.0, v2
	v_rcp_f32_e32 v2, v2
	s_nop 0
	v_mul_f32_e32 v2, v3, v2
	v_mul_f32_e32 v2, v23, v2
	v_cvt_pk_bf16_f32 v1, v1, v2
	v_lshl_add_u64 v[2:3], v[48:49], 1, s[86:87]
	v_lshl_add_u64 v[2:3], v[50:51], 1, v[2:3]
	global_store_dwordx2 v[2:3], v[0:1], off
	s_andn2_b64 exec, exec, s[46:47]
	s_cbranch_execz .LBB0_1089
.LBB0_1073:
	s_mov_b32 s5, 0xaaaaaaab
	v_mul_hi_u32 v0, v180, s5
	v_lshrrev_b32_e32 v58, 9, v0
	v_mul_u32_u24_e32 v1, 0xc00, v58
	v_mul_u32_u24_e32 v48, 0x1800, v58
	v_sub_u32_e32 v50, v56, v1
	v_sub_u32_e32 v0, v185, v48
	v_and_b32_e32 v1, 0x7c, v50
	v_and_or_b32 v4, v0, s48, v1
	v_lshl_add_u64 v[8:9], v[48:49], 2, s[28:29]
	v_ashrrev_i32_e32 v5, 31, v4
	v_lshl_add_u64 v[52:53], v[4:5], 2, v[8:9]
	s_mov_b32 s5, 0x600000
	v_add_co_u32_e32 v12, vcc, s5, v52
	s_mov_b32 s5, 0xc00000
	s_nop 0
	v_addc_co_u32_e32 v13, vcc, 0, v53, vcc
	v_add_co_u32_e32 v16, vcc, s5, v52
	s_mov_b32 s5, 0x1200000
	s_nop 0
	v_addc_co_u32_e32 v17, vcc, 0, v53, vcc
	v_ashrrev_i32_e32 v51, 31, v50
	v_add_co_u32_e32 v20, vcc, s5, v52
	v_lshl_add_u64 v[6:7], v[50:51], 2, s[72:73]
	s_nop 0
	v_addc_co_u32_e32 v21, vcc, 0, v53, vcc
	v_add_co_u32_e32 v4, vcc, 0x3000, v6
	global_load_dwordx4 v[0:3], v[6:7], off
	s_nop 0
	v_addc_co_u32_e32 v5, vcc, 0, v7, vcc
	global_load_dwordx4 v[4:7], v[4:5], off
	s_nop 0
	global_load_dwordx4 v[36:39], v[52:53], off
	global_load_dwordx4 v[8:11], v[52:53], off offset:512
	global_load_dwordx4 v[32:35], v[12:13], off
	s_nop 0
	global_load_dwordx4 v[12:15], v[12:13], off offset:512
	s_nop 0
	global_load_dwordx4 v[28:31], v[16:17], off
	s_nop 0
	global_load_dwordx4 v[16:19], v[16:17], off offset:512
	s_nop 0
	global_load_dwordx4 v[24:27], v[20:21], off
	s_nop 0
	global_load_dwordx4 v[20:23], v[20:21], off offset:512
	s_mov_b64 s[98:99], 0
	s_mov_b64 s[100:101], 0
	v_lshlrev_b64 v[116:117], 2, v[50:51]
	v_lshl_add_u64 v[118:119], s[74:75], 0, v[116:117]
	v_lshl_add_u64 v[120:121], s[76:77], 0, v[116:117]
	v_lshl_add_u64 v[122:123], s[36:37], 0, v[116:117]
	v_lshl_add_u64 v[124:125], s[58:59], 0, v[116:117]
	global_load_dwordx4 v[100:103], v[118:119], off
	global_load_dwordx4 v[104:107], v[120:121], off
	global_load_dwordx4 v[108:111], v[122:123], off
	global_load_dwordx4 v[112:115], v[124:125], off
	v_or_b32_e32 v57, 0x4000, v58
	s_movk_i32 s5, 0x4080
	v_cmp_gt_u32_e32 vcc, s5, v57
	s_mov_b64 s[52:53], 0
	s_and_saveexec_b64 s[6:7], vcc
	s_xor_b64 s[50:51], exec, s[6:7]
	s_cbranch_execz .LBB0_1085
	s_mov_b64 s[6:7], 0x2ff
	v_cmp_lt_u64_e32 vcc, s[6:7], v[180:181]
	s_and_saveexec_b64 s[6:7], vcc
	s_xor_b64 s[52:53], exec, s[6:7]
	s_cbranch_execz .LBB0_1076
	s_mov_b64 s[98:99], exec
	v_add_co_u32_e32 v126, vcc, 0xffffa000, v52
	s_nop 1
	v_addc_co_u32_e32 v127, vcc, -1, v53, vcc
	v_add_co_u32_e32 v128, vcc, 0x5fa000, v52
	s_nop 1
	v_addc_co_u32_e32 v129, vcc, 0, v53, vcc
	v_add_co_u32_e32 v130, vcc, 0xbfa000, v52
	s_nop 1
	v_addc_co_u32_e32 v131, vcc, 0, v53, vcc
	v_add_co_u32_e32 v132, vcc, 0x11fa000, v52
	s_nop 1
	v_addc_co_u32_e32 v133, vcc, 0, v53, vcc
	global_load_dwordx4 v[68:71], v[126:127], off
	global_load_dwordx4 v[72:75], v[128:129], off
	global_load_dwordx4 v[76:79], v[130:131], off
	global_load_dwordx4 v[80:83], v[132:133], off

.LBB0_1080:
	s_andn2_saveexec_b64 s[52:53], s[34:35]
	s_cbranch_execz .LBB0_1082
	s_mov_b64 s[100:101], exec
	v_add_co_u32_e32 v134, vcc, 0xffff4000, v52
	s_nop 1
	v_addc_co_u32_e32 v135, vcc, -1, v53, vcc
	v_add_co_u32_e32 v136, vcc, 0x5f4000, v52
	s_nop 1
	v_addc_co_u32_e32 v137, vcc, 0, v53, vcc
	v_add_co_u32_e32 v138, vcc, 0xbf4000, v52
	s_nop 1
	v_addc_co_u32_e32 v139, vcc, 0, v53, vcc
	v_add_co_u32_e32 v140, vcc, 0x11f4000, v52
	s_nop 1
	v_addc_co_u32_e32 v141, vcc, 0, v53, vcc
	global_load_dwordx4 v[84:87], v[134:135], off
	global_load_dwordx4 v[88:91], v[136:137], off
	global_load_dwordx4 v[92:95], v[138:139], off
	global_load_dwordx4 v[96:99], v[140:141], off

.LBB0_1085:
	s_andn2_saveexec_b64 s[50:51], s[50:51]
	s_cbranch_execz .LBB0_1087
	v_readlane_b32 s8, v250, 51
	v_lshlrev_b32_e32 v48, 1, v58
	v_readlane_b32 s20, v250, 63
	v_readlane_b32 s21, v249, 0
	v_lshl_add_u64 v[52:53], v[48:49], 0, s[48:49]
	v_and_b32_e32 v48, 1, v53
	s_nop 0
	v_mov_b64_e32 v[40:41], s[20:21]
	v_mad_u64_u32 v[40:41], s[6:7], v52, s4, v[40:41]
	v_mad_u32_u24 v41, v48, s4, v41
	v_lshl_add_u64 v[40:41], v[50:51], 2, v[40:41]
	v_add_co_u32_e32 v42, vcc, 0x3000, v40
	v_mov_b64_e32 v[54:55], s[44:45]
	s_nop 0
	v_addc_co_u32_e32 v43, vcc, 0, v41, vcc
	global_load_dwordx4 v[44:47], v[40:41], off
	s_nop 0
	global_load_dwordx4 v[40:43], v[42:43], off
	v_mad_u64_u32 v[52:53], s[6:7], v52, s4, v[54:55]
	v_mad_u32_u24 v53, v48, s4, v53
	s_mov_b64 s[6:7], 0x3000
	v_readlane_b32 s9, v250, 52
	v_readlane_b32 s10, v250, 53
	v_readlane_b32 s11, v250, 54
	v_readlane_b32 s12, v250, 55
	v_readlane_b32 s13, v250, 56
	v_readlane_b32 s14, v250, 57
	v_readlane_b32 s15, v250, 58
	v_readlane_b32 s16, v250, 59
	v_readlane_b32 s17, v250, 60
	v_readlane_b32 s18, v250, 61
	v_readlane_b32 s19, v250, 62
	v_readlane_b32 s22, v249, 1
	v_readlane_b32 s23, v249, 2
	v_lshl_add_u64 v[54:55], v[52:53], 0, s[6:7]
	s_or_b64 s[52:53], s[52:53], exec
.LBB0_1087:
	s_or_b64 exec, exec, s[50:51]
	s_waitcnt vmcnt(0)
	s_and_saveexec_b64 s[6:7], s[98:99]
	v_pk_add_f32 v[60:61], v[0:1], v[68:69]
	v_pk_add_f32 v[62:63], v[2:3], v[70:71]
	v_pk_add_f32 v[60:61], v[60:61], v[72:73]
	v_pk_add_f32 v[62:63], v[62:63], v[74:75]
	v_pk_add_f32 v[60:61], v[60:61], v[76:77]
	v_pk_add_f32 v[62:63], v[62:63], v[78:79]
	v_pk_add_f32 v[40:41], v[60:61], v[80:81]
	v_pk_add_f32 v[42:43], v[62:63], v[82:83]
	s_or_b64 exec, exec, s[6:7]
	s_and_saveexec_b64 s[6:7], s[100:101]
	v_pk_add_f32 v[60:61], v[0:1], v[84:85]
	v_pk_add_f32 v[62:63], v[2:3], v[86:87]
	v_pk_add_f32 v[60:61], v[60:61], v[88:89]
	v_pk_add_f32 v[62:63], v[62:63], v[90:91]
	v_pk_add_f32 v[60:61], v[60:61], v[92:93]
	v_pk_add_f32 v[62:63], v[62:63], v[94:95]
	v_pk_add_f32 v[44:45], v[60:61], v[96:97]
	v_pk_add_f32 v[46:47], v[62:63], v[98:99]
	s_or_b64 exec, exec, s[6:7]
	v_pk_add_f32 v[2:3], v[2:3], v[38:39]
	v_pk_add_f32 v[0:1], v[0:1], v[36:37]
	s_nop 0
	v_pk_add_f32 v[2:3], v[2:3], v[34:35]
	v_pk_add_f32 v[0:1], v[0:1], v[32:33]
	s_nop 0
	v_pk_add_f32 v[2:3], v[2:3], v[30:31]
	v_pk_add_f32 v[0:1], v[0:1], v[28:29]
	s_nop 0
	v_pk_add_f32 v[2:3], v[2:3], v[26:27]
	v_pk_add_f32 v[0:1], v[0:1], v[24:25]
	s_and_saveexec_b64 s[34:35], s[52:53]
	s_cbranch_execz .LBB0_1072
	v_lshl_add_u64 v[24:25], v[50:51], 2, v[54:55]
	global_store_dwordx4 v[24:25], v[0:3], off
	s_branch .LBB0_1072

	.amdhsa_kernel _Z8hawk_fwd1P
		.amdhsa_group_segment_fixed_size 0
		.amdhsa_private_segment_fixed_size 0
		.amdhsa_kernarg_size 600
		.amdhsa_user_sgpr_count 2
		.amdhsa_user_sgpr_dispatch_ptr 0
		.amdhsa_user_sgpr_queue_ptr 0
		.amdhsa_user_sgpr_kernarg_segment_ptr 1
		.amdhsa_user_sgpr_dispatch_id 0
		.amdhsa_user_sgpr_kernarg_preload_length 0
		.amdhsa_user_sgpr_kernarg_preload_offset 0
		.amdhsa_user_sgpr_private_segment_size 0
		.amdhsa_uses_dynamic_stack 0
		.amdhsa_enable_private_segment 0
		.amdhsa_system_sgpr_workgroup_id_x 1
		.amdhsa_system_sgpr_workgroup_id_y 0
		.amdhsa_system_sgpr_workgroup_id_z 0
		.amdhsa_system_sgpr_workgroup_info 0
		.amdhsa_system_vgpr_workitem_id 2
		.amdhsa_next_free_vgpr 251
		.amdhsa_next_free_sgpr 102
		.amdhsa_accum_offset 252
		.amdhsa_reserve_vcc 1
		.amdhsa_float_round_mode_32 0
		.amdhsa_float_round_mode_16_64 0
		.amdhsa_float_denorm_mode_32 3
		.amdhsa_float_denorm_mode_16_64 3
		.amdhsa_dx10_clamp 1
		.amdhsa_ieee_mode 1
		.amdhsa_fp16_overflow 0
		.amdhsa_tg_split 0
		.amdhsa_exception_fp_ieee_invalid_op 0
		.amdhsa_exception_fp_denorm_src 0
		.amdhsa_exception_fp_ieee_div_zero 0
		.amdhsa_exception_fp_ieee_overflow 0
		.amdhsa_exception_fp_ieee_underflow 0
		.amdhsa_exception_fp_ieee_inexact 0
		.amdhsa_exception_int_div_zero 0
	.end_amdhsa_kernel

amdhsa.kernels:
  - .agpr_count:     0
    .args:
      - .offset:         0
        .size:           344
        .value_kind:     by_value
      - .offset:         344
        .size:           4
        .value_kind:     hidden_block_count_x
      - .offset:         348
        .size:           4
        .value_kind:     hidden_block_count_y
      - .offset:         352
        .size:           4
        .value_kind:     hidden_block_count_z
      - .offset:         356
        .size:           2
        .value_kind:     hidden_group_size_x
      - .offset:         358
        .size:           2
        .value_kind:     hidden_group_size_y
      - .offset:         360
        .size:           2
        .value_kind:     hidden_group_size_z
      - .offset:         362
        .size:           2
        .value_kind:     hidden_remainder_x
      - .offset:         364
        .size:           2
        .value_kind:     hidden_remainder_y
      - .offset:         366
        .size:           2
        .value_kind:     hidden_remainder_z
      - .offset:         384
        .size:           8
        .value_kind:     hidden_global_offset_x
      - .offset:         392
        .size:           8
        .value_kind:     hidden_global_offset_y
      - .offset:         400
        .size:           8
        .value_kind:     hidden_global_offset_z
      - .offset:         408
        .size:           2
        .value_kind:     hidden_grid_dims
      - .offset:         432
        .size:           8
        .value_kind:     hidden_multigrid_sync_arg
      - .offset:         464
        .size:           4
        .value_kind:     hidden_dynamic_lds_size
    .group_segment_fixed_size: 0
    .kernarg_segment_align: 8
    .kernarg_segment_size: 600
    .language:       OpenCL C
    .language_version:
      - 2
      - 0
    .max_flat_workgroup_size: 512
    .name:           _Z8hawk_fwd1P
    .private_segment_fixed_size: 0
    .sgpr_count:     108
    .sgpr_spill_count: 188
    .symbol:         _Z8hawk_fwd1P.kd
    .uniform_work_group_size: 1
    .uses_dynamic_stack: false
    .vgpr_count:     251
    .vgpr_spill_count: 0
    .wavefront_size: 64
